# grid barrier hand-written at all 4 sites: XCD last arriver adds to a slot word per XCD, every workgroup polls only its own XCD slot (no top-level election, one poll hop); nloc/nx discovery once
# speedup vs baseline: 1.0048x; 1.0048x over previous
.LBB0_489:
	s_getreg_b32 s6, hwreg(HW_REG_XCC_ID, 0, 4)
	s_waitcnt vmcnt(0)
	s_barrier
	s_and_saveexec_b64 s[4:5], s[74:75]
	s_cbranch_execz .LBB0_541
	v_readlane_b32 s7, v255, 10
	v_readlane_b32 s8, v255, 11
	s_and_b32 s6, s6, 15
	s_lshl_b32 s6, s6, 8
	v_mov_b32_e32 v0, s7
	v_mov_b32_e32 v2, s8
	ds_read_b32 v3, v0
	ds_read_b32 v2, v2
	s_add_i32 s9, s6, 0x1400
	s_add_i32 s10, s6, 0x4000
	s_waitcnt vmcnt(0) lgkmcnt(0)
	v_mov_b32_e32 v0, s9
	v_mov_b32_e32 v4, 1
	global_atomic_add v4, v0, v4, s[36:37] sc0
	v_cvt_f32_u32_e32 v5, v3
	v_rcp_f32_e32 v5, v5
	s_waitcnt vmcnt(0)
	v_cvt_f32_u32_e32 v0, v4
	v_add_f32_e32 v0, 0.5, v0
	v_mul_f32_e32 v0, v0, v5
	v_cvt_u32_f32_e32 v0, v0
	v_add_u32_e32 v0, 1, v0
	v_mul_lo_u32 v5, v0, v3
	v_mul_lo_u32 v2, v0, v2
	v_add_u32_e32 v4, 1, v4
	v_mov_b32_e32 v0, s10
	v_cmp_ne_u32_e32 vcc, v4, v5
	s_cbranch_vccnz .Lmy_xb0_poll
	buffer_wbl2 sc1
	s_waitcnt vmcnt(0)
	v_mov_b32_e32 v4, 1
	v_mov_b32_e32 v3, 0x4000
	global_atomic_add v3, v4, s[36:37]
	v_mov_b32_e32 v3, 0x4100
	global_atomic_add v3, v4, s[36:37]
	v_mov_b32_e32 v3, 0x4200
	global_atomic_add v3, v4, s[36:37]
	v_mov_b32_e32 v3, 0x4300
	global_atomic_add v3, v4, s[36:37]
	v_mov_b32_e32 v3, 0x4400
	global_atomic_add v3, v4, s[36:37]
	v_mov_b32_e32 v3, 0x4500
	global_atomic_add v3, v4, s[36:37]
	v_mov_b32_e32 v3, 0x4600
	global_atomic_add v3, v4, s[36:37]
	v_mov_b32_e32 v3, 0x4700
	global_atomic_add v3, v4, s[36:37]
	v_mov_b32_e32 v3, 0x4800
	global_atomic_add v3, v4, s[36:37]
	v_mov_b32_e32 v3, 0x4900
	global_atomic_add v3, v4, s[36:37]
	v_mov_b32_e32 v3, 0x4a00
	global_atomic_add v3, v4, s[36:37]
	v_mov_b32_e32 v3, 0x4b00
	global_atomic_add v3, v4, s[36:37]
	v_mov_b32_e32 v3, 0x4c00
	global_atomic_add v3, v4, s[36:37]
	v_mov_b32_e32 v3, 0x4d00
	global_atomic_add v3, v4, s[36:37]
	v_mov_b32_e32 v3, 0x4e00
	global_atomic_add v3, v4, s[36:37]
	v_mov_b32_e32 v3, 0x4f00
	global_atomic_add v3, v4, s[36:37]

.Lmy_xb0_spin:
	global_load_dword v3, v0, s[36:37] sc1
	s_waitcnt vmcnt(0)
	v_sub_u32_e32 v3, v3, v2
	v_cmp_gt_i32_e32 vcc, 0, v3
	s_cbranch_vccz .Lmy_xb0_acq
	s_sleep 1
	s_add_i32 s12, s12, 1
	s_cmp_lt_u32 s12, 0x40000
	s_cbranch_scc1 .Lmy_xb0_spin

.LBB0_854:
	s_getreg_b32 s6, hwreg(HW_REG_XCC_ID, 0, 4)
	s_waitcnt vmcnt(0)
	s_waitcnt vmcnt(0)
	s_barrier
	s_and_saveexec_b64 s[4:5], s[74:75]
	v_readlane_b32 s26, v254, 28
	v_readlane_b32 s57, v254, 29
	v_readlane_b32 s68, v254, 30
	v_readlane_b32 s69, v255, 7
	v_readlane_b32 s72, v255, 8
	s_mov_b32 s27, 0x600000
	s_movk_i32 s95, 0xc00
	s_cbranch_execz .LBB0_906
	v_readlane_b32 s7, v255, 10
	v_readlane_b32 s8, v255, 11
	s_and_b32 s6, s6, 15
	s_lshl_b32 s6, s6, 8
	v_mov_b32_e32 v0, s7
	v_mov_b32_e32 v2, s8
	ds_read_b32 v3, v0
	ds_read_b32 v2, v2
	s_add_i32 s9, s6, 0x1400
	s_add_i32 s10, s6, 0x4000
	s_waitcnt vmcnt(0) lgkmcnt(0)
	v_cmp_ne_u32_e32 vcc, 0, v3
	s_cbranch_vccnz .Lmy_xb1_have
	s_mov_b32 s12, 0
.Lmy_xb1_disc:
	v_mov_b32_e32 v0, 0x400
	global_load_dword v2, v0, s[36:37] sc1
	global_load_dword v3, v0, s[36:37] offset:256 sc1
	global_load_dword v4, v0, s[36:37] offset:512 sc1
	global_load_dword v5, v0, s[36:37] offset:768 sc1
	global_load_dword v6, v0, s[36:37] offset:1024 sc1
	global_load_dword v7, v0, s[36:37] offset:1280 sc1
	global_load_dword v8, v0, s[36:37] offset:1536 sc1
	global_load_dword v9, v0, s[36:37] offset:1792 sc1
	global_load_dword v10, v0, s[36:37] offset:2048 sc1
	global_load_dword v11, v0, s[36:37] offset:2304 sc1
	global_load_dword v12, v0, s[36:37] offset:2560 sc1
	global_load_dword v13, v0, s[36:37] offset:2816 sc1
	global_load_dword v14, v0, s[36:37] offset:3072 sc1
	global_load_dword v15, v0, s[36:37] offset:3328 sc1
	global_load_dword v16, v0, s[36:37] offset:3584 sc1
	global_load_dword v17, v0, s[36:37] offset:3840 sc1
	s_mov_b32 s7, 0
	s_mov_b32 s8, 0
	s_waitcnt vmcnt(0)
	v_readfirstlane_b32 s13, v2
	s_add_i32 s7, s7, s13
	s_cmp_lg_u32 s13, 0
	s_addc_u32 s8, s8, 0
	v_readfirstlane_b32 s13, v3
	s_add_i32 s7, s7, s13
	s_cmp_lg_u32 s13, 0
	s_addc_u32 s8, s8, 0
	v_readfirstlane_b32 s13, v4
	s_add_i32 s7, s7, s13
	s_cmp_lg_u32 s13, 0
	s_addc_u32 s8, s8, 0
	v_readfirstlane_b32 s13, v5
	s_add_i32 s7, s7, s13
	s_cmp_lg_u32 s13, 0
	s_addc_u32 s8, s8, 0
	v_readfirstlane_b32 s13, v6
	s_add_i32 s7, s7, s13
	s_cmp_lg_u32 s13, 0
	s_addc_u32 s8, s8, 0
	v_readfirstlane_b32 s13, v7
	s_add_i32 s7, s7, s13
	s_cmp_lg_u32 s13, 0
	s_addc_u32 s8, s8, 0
	v_readfirstlane_b32 s13, v8
	s_add_i32 s7, s7, s13
	s_cmp_lg_u32 s13, 0
	s_addc_u32 s8, s8, 0
	v_readfirstlane_b32 s13, v9
	s_add_i32 s7, s7, s13
	s_cmp_lg_u32 s13, 0
	s_addc_u32 s8, s8, 0
	v_readfirstlane_b32 s13, v10
	s_add_i32 s7, s7, s13
	s_cmp_lg_u32 s13, 0
	s_addc_u32 s8, s8, 0
	v_readfirstlane_b32 s13, v11
	s_add_i32 s7, s7, s13
	s_cmp_lg_u32 s13, 0
	s_addc_u32 s8, s8, 0
	v_readfirstlane_b32 s13, v12
	s_add_i32 s7, s7, s13
	s_cmp_lg_u32 s13, 0
	s_addc_u32 s8, s8, 0
	v_readfirstlane_b32 s13, v13
	s_add_i32 s7, s7, s13
	s_cmp_lg_u32 s13, 0
	s_addc_u32 s8, s8, 0
	v_readfirstlane_b32 s13, v14
	s_add_i32 s7, s7, s13
	s_cmp_lg_u32 s13, 0
	s_addc_u32 s8, s8, 0
	v_readfirstlane_b32 s13, v15
	s_add_i32 s7, s7, s13
	s_cmp_lg_u32 s13, 0
	s_addc_u32 s8, s8, 0
	v_readfirstlane_b32 s13, v16
	s_add_i32 s7, s7, s13
	s_cmp_lg_u32 s13, 0
	s_addc_u32 s8, s8, 0
	v_readfirstlane_b32 s13, v17
	s_add_i32 s7, s7, s13
	s_cmp_lg_u32 s13, 0
	s_addc_u32 s8, s8, 0
	s_cmp_eq_u32 s7, s35
	s_cbranch_scc1 .Lmy_xb1_disc_ok
	s_sleep 1
	s_add_i32 s12, s12, 1
	s_cmp_lt_u32 s12, 0x40000
	s_cbranch_scc1 .Lmy_xb1_disc
.Lmy_xb1_disc_ok:
	s_add_i32 s13, s6, 0x400
	v_mov_b32_e32 v0, s13
	global_load_dword v3, v0, s[36:37] sc1
	s_max_u32 s8, s8, 1
	v_mov_b32_e32 v2, s8
	v_readlane_b32 s7, v255, 10
	v_readlane_b32 s13, v255, 11
	v_mov_b32_e32 v4, s7
	v_mov_b32_e32 v5, s13
	s_waitcnt vmcnt(0)
	v_max_u32_e32 v3, 1, v3
	ds_write_b32 v4, v3
	ds_write_b32 v5, v2
.Lmy_xb1_have:
	v_mov_b32_e32 v0, s9
	v_mov_b32_e32 v4, 1
	global_atomic_add v4, v0, v4, s[36:37] sc0
	v_cvt_f32_u32_e32 v5, v3
	v_rcp_f32_e32 v5, v5
	s_waitcnt vmcnt(0)
	v_cvt_f32_u32_e32 v0, v4
	v_add_f32_e32 v0, 0.5, v0
	v_mul_f32_e32 v0, v0, v5
	v_cvt_u32_f32_e32 v0, v0
	v_add_u32_e32 v0, 1, v0
	v_mul_lo_u32 v5, v0, v3
	v_mul_lo_u32 v2, v0, v2
	v_add_u32_e32 v4, 1, v4
	v_mov_b32_e32 v0, s10
	v_cmp_ne_u32_e32 vcc, v4, v5
	s_cbranch_vccnz .Lmy_xb1_poll
	buffer_wbl2 sc1
	s_waitcnt vmcnt(0)
	v_mov_b32_e32 v4, 1
	v_mov_b32_e32 v3, 0x4000
	global_atomic_add v3, v4, s[36:37]
	v_mov_b32_e32 v3, 0x4100
	global_atomic_add v3, v4, s[36:37]
	v_mov_b32_e32 v3, 0x4200
	global_atomic_add v3, v4, s[36:37]
	v_mov_b32_e32 v3, 0x4300
	global_atomic_add v3, v4, s[36:37]
	v_mov_b32_e32 v3, 0x4400
	global_atomic_add v3, v4, s[36:37]
	v_mov_b32_e32 v3, 0x4500
	global_atomic_add v3, v4, s[36:37]
	v_mov_b32_e32 v3, 0x4600
	global_atomic_add v3, v4, s[36:37]
	v_mov_b32_e32 v3, 0x4700
	global_atomic_add v3, v4, s[36:37]
	v_mov_b32_e32 v3, 0x4800
	global_atomic_add v3, v4, s[36:37]
	v_mov_b32_e32 v3, 0x4900
	global_atomic_add v3, v4, s[36:37]
	v_mov_b32_e32 v3, 0x4a00
	global_atomic_add v3, v4, s[36:37]
	v_mov_b32_e32 v3, 0x4b00
	global_atomic_add v3, v4, s[36:37]
	v_mov_b32_e32 v3, 0x4c00
	global_atomic_add v3, v4, s[36:37]
	v_mov_b32_e32 v3, 0x4d00
	global_atomic_add v3, v4, s[36:37]
	v_mov_b32_e32 v3, 0x4e00
	global_atomic_add v3, v4, s[36:37]
	v_mov_b32_e32 v3, 0x4f00
	global_atomic_add v3, v4, s[36:37]

.Lmy_xb1_acq:
	buffer_inv sc1
	s_waitcnt vmcnt(0)
.LBB0_906:
	s_or_b64 exec, exec, s[4:5]
	s_mov_b64 s[4:5], -1
	s_and_b64 vcc, exec, s[58:59]
	s_waitcnt lgkmcnt(0)
	s_barrier
	s_cbranch_vccz .LBB0_926
	v_readlane_b32 s4, v254, 22
	v_readlane_b32 s5, v254, 23
	v_mov_b32_e32 v98, v237
	s_andn2_b64 vcc, exec, s[4:5]
	s_cbranch_vccnz .LBB0_925
	s_load_dwordx2 s[4:5], s[0:1], 0x50
	s_mov_b32 s29, s43
	s_lshl_b64 s[6:7], s[28:29], 12
	v_ashrrev_i32_e32 v0, 7, v98
	v_mul_lo_u32 v2, v0, 6
	s_waitcnt lgkmcnt(0)
	s_add_u32 s6, s4, s6
	s_addc_u32 s7, s5, s7
	v_readlane_b32 s4, v254, 36
	v_ashrrev_i32_e32 v3, 31, v2
	v_and_b32_e32 v100, 0x7f, v98
	v_readlane_b32 s5, v254, 37
	v_lshlrev_b64 v[102:103], 15, v[2:3]
	v_or_b32_e32 v2, 1, v2
	v_or_b32_e32 v4, s4, v100
	v_mov_b32_e32 v5, s5
	v_ashrrev_i32_e32 v3, 31, v2
	v_lshl_add_u64 v[6:7], v[102:103], 0, v[4:5]
	v_readlane_b32 s8, v254, 18
	v_readlane_b32 s10, v254, 20
	v_lshlrev_b64 v[106:107], 15, v[2:3]
	v_lshlrev_b64 v[6:7], 2, v[6:7]
	v_readlane_b32 s9, v254, 19
	v_readlane_b32 s11, v254, 21
	v_lshl_add_u64 v[2:3], v[106:107], 0, v[4:5]
	v_lshl_add_u64 v[8:9], s[8:9], 0, v[6:7]
	v_lshl_add_u64 v[6:7], s[10:11], 0, v[6:7]
	v_lshlrev_b64 v[2:3], 2, v[2:3]
	s_mov_b64 s[4:5], 0x10000
	global_load_dword v105, v[6:7], off
	v_lshl_add_u64 v[6:7], s[8:9], 0, v[2:3]
	v_lshl_add_u64 v[2:3], s[10:11], 0, v[2:3]
	v_lshl_add_u64 v[108:109], v[102:103], 0, s[4:5]
	global_load_dword v112, v[6:7], off
	global_load_dword v113, v[2:3], off
	v_lshl_add_u64 v[2:3], v[108:109], 0, v[4:5]
	v_lshlrev_b64 v[2:3], 2, v[2:3]
	s_mov_b64 s[4:5], 0x18000
	v_lshl_add_u64 v[6:7], s[8:9], 0, v[2:3]
	v_lshl_add_u64 v[2:3], s[10:11], 0, v[2:3]
	v_lshl_add_u64 v[110:111], v[102:103], 0, s[4:5]
	global_load_dword v114, v[6:7], off
	global_load_dword v115, v[2:3], off
	v_lshl_add_u64 v[2:3], v[110:111], 0, v[4:5]
	v_lshlrev_b64 v[2:3], 2, v[2:3]
	s_mov_b64 s[4:5], 0x20000
	v_lshl_add_u64 v[6:7], s[8:9], 0, v[2:3]
	v_lshl_add_u64 v[2:3], s[10:11], 0, v[2:3]
	v_lshl_add_u64 v[116:117], v[102:103], 0, s[4:5]
	global_load_dword v120, v[6:7], off
	global_load_dword v121, v[2:3], off
	v_lshl_add_u64 v[2:3], v[116:117], 0, v[4:5]
	v_lshlrev_b64 v[2:3], 2, v[2:3]
	s_mov_b64 s[4:5], 0x28000
	v_lshl_add_u64 v[6:7], s[8:9], 0, v[2:3]
	v_lshl_add_u64 v[2:3], s[10:11], 0, v[2:3]
	v_lshl_add_u64 v[118:119], v[102:103], 0, s[4:5]
	global_load_dword v122, v[6:7], off
	global_load_dword v123, v[2:3], off
	v_lshl_add_u64 v[2:3], v[118:119], 0, v[4:5]
	v_lshlrev_b64 v[2:3], 2, v[2:3]
	v_lshl_add_u64 v[4:5], s[8:9], 0, v[2:3]
	v_lshl_add_u64 v[2:3], s[10:11], 0, v[2:3]
	global_load_dword v104, v[8:9], off
	global_load_dword v128, v[4:5], off
	global_load_dword v129, v[2:3], off
	s_movk_i32 s4, 0x80
	v_cmp_gt_i32_e64 s[4:5], s4, v98
	v_mov_b32_e32 v99, 0
	s_and_saveexec_b64 s[8:9], s[4:5]
	s_cbranch_execz .LBB0_910
	v_ashrrev_i32_e32 v99, 31, v98
	v_lshl_add_u64 v[2:3], v[98:99], 2, s[6:7]
	global_load_dword v99, v[2:3], off

.LBB0_974:
	s_getreg_b32 s6, hwreg(HW_REG_XCC_ID, 0, 4)
	s_waitcnt vmcnt(0)
	s_waitcnt lgkmcnt(0)
	s_barrier
	s_and_saveexec_b64 s[4:5], s[74:75]
	s_cbranch_execz .LBB0_1026
	v_readlane_b32 s7, v255, 10
	v_readlane_b32 s8, v255, 11
	s_and_b32 s6, s6, 15
	s_lshl_b32 s6, s6, 8
	v_mov_b32_e32 v0, s7
	v_mov_b32_e32 v2, s8
	ds_read_b32 v3, v0
	ds_read_b32 v2, v2
	s_add_i32 s9, s6, 0x1400
	s_add_i32 s10, s6, 0x4000
	s_waitcnt vmcnt(0) lgkmcnt(0)
	v_mov_b32_e32 v0, s9
	v_mov_b32_e32 v4, 1
	global_atomic_add v4, v0, v4, s[36:37] sc0
	v_cvt_f32_u32_e32 v5, v3
	v_rcp_f32_e32 v5, v5
	s_waitcnt vmcnt(0)
	v_cvt_f32_u32_e32 v0, v4
	v_add_f32_e32 v0, 0.5, v0
	v_mul_f32_e32 v0, v0, v5
	v_cvt_u32_f32_e32 v0, v0
	v_add_u32_e32 v0, 1, v0
	v_mul_lo_u32 v5, v0, v3
	v_mul_lo_u32 v2, v0, v2
	v_add_u32_e32 v4, 1, v4
	v_mov_b32_e32 v0, s10
	v_cmp_ne_u32_e32 vcc, v4, v5
	s_cbranch_vccnz .Lmy_xb2_poll
	buffer_wbl2 sc1
	s_waitcnt vmcnt(0)
	v_mov_b32_e32 v4, 1
	v_mov_b32_e32 v3, 0x4000
	global_atomic_add v3, v4, s[36:37]
	v_mov_b32_e32 v3, 0x4100
	global_atomic_add v3, v4, s[36:37]
	v_mov_b32_e32 v3, 0x4200
	global_atomic_add v3, v4, s[36:37]
	v_mov_b32_e32 v3, 0x4300
	global_atomic_add v3, v4, s[36:37]
	v_mov_b32_e32 v3, 0x4400
	global_atomic_add v3, v4, s[36:37]
	v_mov_b32_e32 v3, 0x4500
	global_atomic_add v3, v4, s[36:37]
	v_mov_b32_e32 v3, 0x4600
	global_atomic_add v3, v4, s[36:37]
	v_mov_b32_e32 v3, 0x4700
	global_atomic_add v3, v4, s[36:37]
	v_mov_b32_e32 v3, 0x4800
	global_atomic_add v3, v4, s[36:37]
	v_mov_b32_e32 v3, 0x4900
	global_atomic_add v3, v4, s[36:37]
	v_mov_b32_e32 v3, 0x4a00
	global_atomic_add v3, v4, s[36:37]
	v_mov_b32_e32 v3, 0x4b00
	global_atomic_add v3, v4, s[36:37]
	v_mov_b32_e32 v3, 0x4c00
	global_atomic_add v3, v4, s[36:37]
	v_mov_b32_e32 v3, 0x4d00
	global_atomic_add v3, v4, s[36:37]
	v_mov_b32_e32 v3, 0x4e00
	global_atomic_add v3, v4, s[36:37]
	v_mov_b32_e32 v3, 0x4f00
	global_atomic_add v3, v4, s[36:37]

.LBB0_1186:
	s_cmp_eq_u32 s40, 7
	v_readlane_b32 s26, v255, 37
	v_readlane_b32 s27, v255, 38
	s_cbranch_scc1 .LBB0_161
	s_getreg_b32 s6, hwreg(HW_REG_XCC_ID, 0, 4)
	s_waitcnt vmcnt(0)
	s_barrier
	s_and_saveexec_b64 s[4:5], s[74:75]
	s_cbranch_execz .LBB0_160
	v_readlane_b32 s7, v255, 10
	v_readlane_b32 s8, v255, 11
	s_and_b32 s6, s6, 15
	s_lshl_b32 s6, s6, 8
	v_mov_b32_e32 v0, s7
	v_mov_b32_e32 v2, s8
	ds_read_b32 v3, v0
	ds_read_b32 v2, v2
	s_add_i32 s9, s6, 0x1400
	s_add_i32 s10, s6, 0x4000
	s_waitcnt vmcnt(0) lgkmcnt(0)
	v_mov_b32_e32 v0, s9
	v_mov_b32_e32 v4, 1
	global_atomic_add v4, v0, v4, s[36:37] sc0
	v_cvt_f32_u32_e32 v5, v3
	v_rcp_f32_e32 v5, v5
	s_waitcnt vmcnt(0)
	v_cvt_f32_u32_e32 v0, v4
	v_add_f32_e32 v0, 0.5, v0
	v_mul_f32_e32 v0, v0, v5
	v_cvt_u32_f32_e32 v0, v0
	v_add_u32_e32 v0, 1, v0
	v_mul_lo_u32 v5, v0, v3
	v_mul_lo_u32 v2, v0, v2
	v_add_u32_e32 v4, 1, v4
	v_mov_b32_e32 v0, s10
	v_cmp_ne_u32_e32 vcc, v4, v5
	s_cbranch_vccnz .Lmy_xb3_poll
	buffer_wbl2 sc1
	s_waitcnt vmcnt(0)
	v_mov_b32_e32 v4, 1
	v_mov_b32_e32 v3, 0x4000
	global_atomic_add v3, v4, s[36:37]
	v_mov_b32_e32 v3, 0x4100
	global_atomic_add v3, v4, s[36:37]
	v_mov_b32_e32 v3, 0x4200
	global_atomic_add v3, v4, s[36:37]
	v_mov_b32_e32 v3, 0x4300
	global_atomic_add v3, v4, s[36:37]
	v_mov_b32_e32 v3, 0x4400
	global_atomic_add v3, v4, s[36:37]
	v_mov_b32_e32 v3, 0x4500
	global_atomic_add v3, v4, s[36:37]
	v_mov_b32_e32 v3, 0x4600
	global_atomic_add v3, v4, s[36:37]
	v_mov_b32_e32 v3, 0x4700
	global_atomic_add v3, v4, s[36:37]
	v_mov_b32_e32 v3, 0x4800
	global_atomic_add v3, v4, s[36:37]
	v_mov_b32_e32 v3, 0x4900
	global_atomic_add v3, v4, s[36:37]
	v_mov_b32_e32 v3, 0x4a00
	global_atomic_add v3, v4, s[36:37]
	v_mov_b32_e32 v3, 0x4b00
	global_atomic_add v3, v4, s[36:37]
	v_mov_b32_e32 v3, 0x4c00
	global_atomic_add v3, v4, s[36:37]
	v_mov_b32_e32 v3, 0x4d00
	global_atomic_add v3, v4, s[36:37]
	v_mov_b32_e32 v3, 0x4e00
	global_atomic_add v3, v4, s[36:37]
	v_mov_b32_e32 v3, 0x4f00
	global_atomic_add v3, v4, s[36:37]
